# hoist row-statistic loads in input-projection epilogue (layer1) and preload final-norm operands: removes 8+16 serialized load-wait-store round trips
# speedup vs baseline: 1.0241x; 1.0241x over previous
.LBB0_199:
	s_add_u32 s26, s40, s0
	s_addc_u32 s27, s41, s1
	s_add_u32 s26, s26, 0x100
	s_addc_u32 s27, s27, 0
	s_add_u32 s42, s23, s0
	s_addc_u32 s43, s24, s1
	s_add_i32 s49, 0, 0x10000
	v_add_u32_e32 v142, s49, v146
	ds_read_b128 v[148:151], v142
	ds_read_b128 v[152:155], v142 offset:1024
	ds_read_b128 v[156:159], v142 offset:2048
	ds_read_b128 v[160:163], v142 offset:3072
	s_cmpk_eq_i32 s0, 0x700
	s_cselect_b32 s45, s69, s27
	s_cselect_b32 s44, s68, s26
	s_cselect_b32 s43, s35, s43
	s_cselect_b32 s42, s34, s42
	v_lshl_add_u64 v[142:143], v[140:141], 0, s[0:1]
	s_add_i32 m0, s18, 0xc000
	ds_read_b128 v[164:167], v147
	ds_read_b128 v[174:177], v147 offset:1024
	ds_read_b128 v[178:181], v147 offset:2048
	ds_read_b128 v[182:185], v147 offset:3072
	ds_read_b128 v[186:189], v147 offset:4096
	ds_read_b128 v[190:193], v147 offset:5120
	ds_read_b128 v[202:205], v147 offset:6144
	ds_read_b128 v[206:209], v147 offset:7168
	global_load_lds_dwordx4 v[142:143], off
	v_lshl_add_u64 v[142:143], v[138:139], 0, s[0:1]
	s_add_i32 m0, s18, 0xe000
	s_nop 0
	global_load_lds_dwordx4 v[142:143], off
	s_waitcnt lgkmcnt(8)
	s_barrier
	s_waitcnt lgkmcnt(0)
	s_setprio 1
	s_waitcnt lgkmcnt(0)
	v_mfma_f32_16x16x32_bf16 v[124:127], v[148:151], v[164:167], v[124:127]
	v_mfma_f32_16x16x32_bf16 v[120:123], v[156:159], v[164:167], v[120:123]
	v_mfma_f32_16x16x32_bf16 v[108:111], v[148:151], v[178:181], v[108:111]
	v_mfma_f32_16x16x32_bf16 v[104:107], v[156:159], v[178:181], v[104:107]
	v_mfma_f32_16x16x32_bf16 v[92:95], v[148:151], v[186:189], v[92:95]
	v_mfma_f32_16x16x32_bf16 v[88:91], v[156:159], v[186:189], v[88:91]
	v_mfma_f32_16x16x32_bf16 v[76:79], v[148:151], v[202:205], v[76:79]
	v_mfma_f32_16x16x32_bf16 v[72:75], v[156:159], v[202:205], v[72:75]
	v_mfma_f32_16x16x32_bf16 v[124:127], v[152:155], v[174:177], v[124:127]
	v_mfma_f32_16x16x32_bf16 v[120:123], v[160:163], v[174:177], v[120:123]
	v_mfma_f32_16x16x32_bf16 v[108:111], v[152:155], v[182:185], v[108:111]
	v_mfma_f32_16x16x32_bf16 v[104:107], v[160:163], v[182:185], v[104:107]
	v_mfma_f32_16x16x32_bf16 v[92:95], v[152:155], v[190:193], v[92:95]
	v_mfma_f32_16x16x32_bf16 v[88:91], v[160:163], v[190:193], v[88:91]
	v_mfma_f32_16x16x32_bf16 v[76:79], v[152:155], v[206:209], v[76:79]
	v_mfma_f32_16x16x32_bf16 v[72:75], v[160:163], v[206:209], v[72:75]
	s_setprio 0
	s_barrier
	s_add_i32 s71, 0, 0x14000
	v_add_u32_e32 v142, s71, v146
	s_add_i32 s26, s49, s17
	ds_read_b128 v[210:213], v142
	ds_read_b128 v[214:217], v142 offset:1024
	ds_read_b128 v[218:221], v142 offset:2048
	ds_read_b128 v[222:225], v142 offset:3072
	v_lshl_add_u64 v[142:143], s[42:43], 0, v[172:173]
	s_mov_b32 m0, s26
	v_lshl_add_u64 v[226:227], s[42:43], 0, v[132:133]
	global_load_lds_dwordx4 v[142:143], off
	s_add_i32 m0, s26, 0x2000
	s_nop 0
	global_load_lds_dwordx4 v[226:227], off
	s_barrier
	s_waitcnt lgkmcnt(0)
	s_setprio 1
	s_waitcnt lgkmcnt(0)
	v_mfma_f32_16x16x32_bf16 v[116:119], v[210:213], v[164:167], v[116:119]
	v_mfma_f32_16x16x32_bf16 v[112:115], v[218:221], v[164:167], v[112:115]
	v_mfma_f32_16x16x32_bf16 v[100:103], v[210:213], v[178:181], v[100:103]
	v_mfma_f32_16x16x32_bf16 v[96:99], v[218:221], v[178:181], v[96:99]
	v_mfma_f32_16x16x32_bf16 v[84:87], v[210:213], v[186:189], v[84:87]
	v_mfma_f32_16x16x32_bf16 v[80:83], v[218:221], v[186:189], v[80:83]
	v_mfma_f32_16x16x32_bf16 v[68:71], v[210:213], v[202:205], v[68:71]
	v_mfma_f32_16x16x32_bf16 v[64:67], v[218:221], v[202:205], v[64:67]
	v_mfma_f32_16x16x32_bf16 v[116:119], v[214:217], v[174:177], v[116:119]
	v_mfma_f32_16x16x32_bf16 v[112:115], v[222:225], v[174:177], v[112:115]
	v_mfma_f32_16x16x32_bf16 v[100:103], v[214:217], v[182:185], v[100:103]
	v_mfma_f32_16x16x32_bf16 v[96:99], v[222:225], v[182:185], v[96:99]
	v_mfma_f32_16x16x32_bf16 v[84:87], v[214:217], v[190:193], v[84:87]
	v_mfma_f32_16x16x32_bf16 v[80:83], v[222:225], v[190:193], v[80:83]
	v_mfma_f32_16x16x32_bf16 v[68:71], v[214:217], v[206:209], v[68:71]
	v_mfma_f32_16x16x32_bf16 v[64:67], v[222:225], v[206:209], v[64:67]
	s_setprio 0
	s_mov_b32 m0, s18
	v_lshl_add_u64 v[228:229], s[44:45], 0, v[128:129]
	s_barrier
	ds_read_b128 v[164:167], v147 offset:16384
	ds_read_b128 v[174:177], v147 offset:17408
	ds_read_b128 v[178:181], v147 offset:18432
	ds_read_b128 v[182:185], v147 offset:19456
	ds_read_b128 v[186:189], v147 offset:20480
	ds_read_b128 v[190:193], v147 offset:21504
	ds_read_b128 v[202:205], v147 offset:22528
	ds_read_b128 v[206:209], v147 offset:23552
	global_load_lds_dwordx4 v[228:229], off
	v_lshl_add_u64 v[230:231], s[44:45], 0, v[130:131]
	s_mov_b32 m0, s19
	s_nop 0
	global_load_lds_dwordx4 v[230:231], off
	s_barrier
	s_waitcnt lgkmcnt(0)
	s_setprio 1
	s_waitcnt lgkmcnt(0)
	v_mfma_f32_16x16x32_bf16 v[60:63], v[148:151], v[164:167], v[60:63]
	v_mfma_f32_16x16x32_bf16 v[56:59], v[156:159], v[164:167], v[56:59]
	v_mfma_f32_16x16x32_bf16 v[44:47], v[148:151], v[178:181], v[44:47]
	v_mfma_f32_16x16x32_bf16 v[40:43], v[156:159], v[178:181], v[40:43]
	v_mfma_f32_16x16x32_bf16 v[28:31], v[148:151], v[186:189], v[28:31]
	v_mfma_f32_16x16x32_bf16 v[24:27], v[156:159], v[186:189], v[24:27]
	v_mfma_f32_16x16x32_bf16 v[12:15], v[148:151], v[202:205], v[12:15]
	v_mfma_f32_16x16x32_bf16 v[8:11], v[156:159], v[202:205], v[8:11]
	v_mfma_f32_16x16x32_bf16 v[60:63], v[152:155], v[174:177], v[60:63]
	v_mfma_f32_16x16x32_bf16 v[56:59], v[160:163], v[174:177], v[56:59]
	v_mfma_f32_16x16x32_bf16 v[44:47], v[152:155], v[182:185], v[44:47]
	v_mfma_f32_16x16x32_bf16 v[40:43], v[160:163], v[182:185], v[40:43]
	v_mfma_f32_16x16x32_bf16 v[28:31], v[152:155], v[190:193], v[28:31]
	v_mfma_f32_16x16x32_bf16 v[24:27], v[160:163], v[190:193], v[24:27]
	v_mfma_f32_16x16x32_bf16 v[12:15], v[152:155], v[206:209], v[12:15]
	v_mfma_f32_16x16x32_bf16 v[8:11], v[160:163], v[206:209], v[8:11]
	s_setprio 0
	s_barrier
	s_add_u32 s26, s42, 0x40000
	s_addc_u32 s27, s43, 0
	s_add_i32 s49, s71, s17
	v_lshl_add_u64 v[148:149], s[26:27], 0, v[172:173]
	s_mov_b32 m0, s49
	s_nop 0
	global_load_lds_dwordx4 v[148:149], off
	v_lshl_add_u64 v[148:149], s[26:27], 0, v[132:133]
	s_add_i32 m0, s49, 0x2000
	s_nop 0
	global_load_lds_dwordx4 v[148:149], off
	s_waitcnt vmcnt(6)
	s_barrier
	s_setprio 1
	v_mfma_f32_16x16x32_bf16 v[52:55], v[210:213], v[164:167], v[52:55]
	v_mfma_f32_16x16x32_bf16 v[48:51], v[218:221], v[164:167], v[48:51]
	v_mfma_f32_16x16x32_bf16 v[36:39], v[210:213], v[178:181], v[36:39]
	v_mfma_f32_16x16x32_bf16 v[32:35], v[218:221], v[178:181], v[32:35]
	v_mfma_f32_16x16x32_bf16 v[20:23], v[210:213], v[186:189], v[20:23]
	v_mfma_f32_16x16x32_bf16 v[16:19], v[218:221], v[186:189], v[16:19]
	v_mfma_f32_16x16x32_bf16 v[4:7], v[210:213], v[202:205], v[4:7]
	v_mfma_f32_16x16x32_bf16 v[0:3], v[218:221], v[202:205], v[0:3]
	v_mfma_f32_16x16x32_bf16 v[52:55], v[214:217], v[174:177], v[52:55]
	v_mfma_f32_16x16x32_bf16 v[48:51], v[222:225], v[174:177], v[48:51]
	v_mfma_f32_16x16x32_bf16 v[36:39], v[214:217], v[182:185], v[36:39]
	v_mfma_f32_16x16x32_bf16 v[32:35], v[222:225], v[182:185], v[32:35]
	v_mfma_f32_16x16x32_bf16 v[20:23], v[214:217], v[190:193], v[20:23]
	v_mfma_f32_16x16x32_bf16 v[16:19], v[222:225], v[190:193], v[16:19]
	v_mfma_f32_16x16x32_bf16 v[4:7], v[214:217], v[206:209], v[4:7]
	v_mfma_f32_16x16x32_bf16 v[0:3], v[222:225], v[206:209], v[0:3]
	s_setprio 0
	s_add_i32 s49, 0, 0x18000
	v_add_u32_e32 v160, s49, v146
	s_barrier
	ds_read_b128 v[148:151], v160
	ds_read_b128 v[152:155], v160 offset:1024
	ds_read_b128 v[156:159], v160 offset:2048
	ds_read_b128 v[160:163], v160 offset:3072
	s_add_u32 s26, s44, s54
	s_addc_u32 s27, s45, 0
	s_mov_b32 m0, s20
	v_lshl_add_u64 v[210:211], s[26:27], 0, v[128:129]
	ds_read_b128 v[164:167], v147 offset:32768
	ds_read_b128 v[174:177], v147 offset:33792
	ds_read_b128 v[178:181], v147 offset:34816
	ds_read_b128 v[182:185], v147 offset:35840
	ds_read_b128 v[186:189], v147 offset:36864
	ds_read_b128 v[190:193], v147 offset:37888
	ds_read_b128 v[202:205], v147 offset:38912
	ds_read_b128 v[206:209], v147 offset:39936
	global_load_lds_dwordx4 v[210:211], off
	v_lshl_add_u64 v[210:211], s[26:27], 0, v[130:131]
	s_mov_b32 m0, s21
	s_nop 0
	global_load_lds_dwordx4 v[210:211], off
	s_waitcnt lgkmcnt(8)
	s_barrier
	s_waitcnt lgkmcnt(0)
	s_setprio 1
	s_waitcnt lgkmcnt(0)
	v_mfma_f32_16x16x32_bf16 v[124:127], v[148:151], v[164:167], v[124:127]
	v_mfma_f32_16x16x32_bf16 v[120:123], v[156:159], v[164:167], v[120:123]
	v_mfma_f32_16x16x32_bf16 v[108:111], v[148:151], v[178:181], v[108:111]
	v_mfma_f32_16x16x32_bf16 v[104:107], v[156:159], v[178:181], v[104:107]
	v_mfma_f32_16x16x32_bf16 v[92:95], v[148:151], v[186:189], v[92:95]
	v_mfma_f32_16x16x32_bf16 v[88:91], v[156:159], v[186:189], v[88:91]
	v_mfma_f32_16x16x32_bf16 v[76:79], v[148:151], v[202:205], v[76:79]
	v_mfma_f32_16x16x32_bf16 v[72:75], v[156:159], v[202:205], v[72:75]
	v_mfma_f32_16x16x32_bf16 v[124:127], v[152:155], v[174:177], v[124:127]
	v_mfma_f32_16x16x32_bf16 v[120:123], v[160:163], v[174:177], v[120:123]
	v_mfma_f32_16x16x32_bf16 v[108:111], v[152:155], v[182:185], v[108:111]
	v_mfma_f32_16x16x32_bf16 v[104:107], v[160:163], v[182:185], v[104:107]
	v_mfma_f32_16x16x32_bf16 v[92:95], v[152:155], v[190:193], v[92:95]
	v_mfma_f32_16x16x32_bf16 v[88:91], v[160:163], v[190:193], v[88:91]
	v_mfma_f32_16x16x32_bf16 v[76:79], v[152:155], v[206:209], v[76:79]
	v_mfma_f32_16x16x32_bf16 v[72:75], v[160:163], v[206:209], v[72:75]
	s_setprio 0
	s_barrier
	s_add_i32 s44, 0, 0x1c000
	s_add_i32 s26, s49, s17
	v_add_u32_e32 v201, s44, v146
	v_lshl_add_u64 v[142:143], v[142:143], 0, s[76:77]
	s_mov_b32 m0, s26
	ds_read_b128 v[210:213], v201
	ds_read_b128 v[214:217], v201 offset:1024
	ds_read_b128 v[218:221], v201 offset:2048
	ds_read_b128 v[222:225], v201 offset:3072
	global_load_lds_dwordx4 v[142:143], off
	v_lshl_add_u64 v[142:143], v[226:227], 0, s[76:77]
	s_add_i32 m0, s26, 0x2000
	s_nop 0
	global_load_lds_dwordx4 v[142:143], off
	s_barrier
	s_waitcnt lgkmcnt(0)
	s_setprio 1
	s_waitcnt lgkmcnt(0)
	v_mfma_f32_16x16x32_bf16 v[116:119], v[210:213], v[164:167], v[116:119]
	v_mfma_f32_16x16x32_bf16 v[112:115], v[218:221], v[164:167], v[112:115]
	v_mfma_f32_16x16x32_bf16 v[100:103], v[210:213], v[178:181], v[100:103]
	v_mfma_f32_16x16x32_bf16 v[96:99], v[218:221], v[178:181], v[96:99]
	v_mfma_f32_16x16x32_bf16 v[84:87], v[210:213], v[186:189], v[84:87]
	v_mfma_f32_16x16x32_bf16 v[80:83], v[218:221], v[186:189], v[80:83]
	v_mfma_f32_16x16x32_bf16 v[68:71], v[210:213], v[202:205], v[68:71]
	v_mfma_f32_16x16x32_bf16 v[64:67], v[218:221], v[202:205], v[64:67]
	v_mfma_f32_16x16x32_bf16 v[116:119], v[214:217], v[174:177], v[116:119]
	v_mfma_f32_16x16x32_bf16 v[112:115], v[222:225], v[174:177], v[112:115]
	v_mfma_f32_16x16x32_bf16 v[100:103], v[214:217], v[182:185], v[100:103]
	v_mfma_f32_16x16x32_bf16 v[96:99], v[222:225], v[182:185], v[96:99]
	v_mfma_f32_16x16x32_bf16 v[84:87], v[214:217], v[190:193], v[84:87]
	v_mfma_f32_16x16x32_bf16 v[80:83], v[222:225], v[190:193], v[80:83]
	v_mfma_f32_16x16x32_bf16 v[68:71], v[214:217], v[206:209], v[68:71]
	v_mfma_f32_16x16x32_bf16 v[64:67], v[222:225], v[206:209], v[64:67]
	s_setprio 0
	s_mov_b32 m0, s60
	v_lshl_add_u64 v[142:143], v[228:229], 0, s[76:77]
	s_barrier
	ds_read_b128 v[164:167], v147 offset:49152
	ds_read_b128 v[174:177], v147 offset:50176
	ds_read_b128 v[178:181], v147 offset:51200
	ds_read_b128 v[182:185], v147 offset:52224
	ds_read_b128 v[186:189], v147 offset:53248
	ds_read_b128 v[190:193], v147 offset:54272
	ds_read_b128 v[202:205], v147 offset:55296
	ds_read_b128 v[206:209], v147 offset:56320
	global_load_lds_dwordx4 v[142:143], off
	v_lshl_add_u64 v[142:143], v[230:231], 0, s[76:77]
	s_mov_b32 m0, s61
	s_nop 0
	global_load_lds_dwordx4 v[142:143], off
	s_barrier
	s_waitcnt lgkmcnt(0)
	s_setprio 1
	s_waitcnt lgkmcnt(0)
	v_mfma_f32_16x16x32_bf16 v[60:63], v[148:151], v[164:167], v[60:63]
	v_mfma_f32_16x16x32_bf16 v[56:59], v[156:159], v[164:167], v[56:59]
	v_mfma_f32_16x16x32_bf16 v[44:47], v[148:151], v[178:181], v[44:47]
	v_mfma_f32_16x16x32_bf16 v[40:43], v[156:159], v[178:181], v[40:43]
	v_mfma_f32_16x16x32_bf16 v[28:31], v[148:151], v[186:189], v[28:31]
	v_mfma_f32_16x16x32_bf16 v[24:27], v[156:159], v[186:189], v[24:27]
	v_mfma_f32_16x16x32_bf16 v[12:15], v[148:151], v[202:205], v[12:15]
	v_mfma_f32_16x16x32_bf16 v[8:11], v[156:159], v[202:205], v[8:11]
	v_mfma_f32_16x16x32_bf16 v[60:63], v[152:155], v[174:177], v[60:63]
	v_mfma_f32_16x16x32_bf16 v[56:59], v[160:163], v[174:177], v[56:59]
	v_mfma_f32_16x16x32_bf16 v[44:47], v[152:155], v[182:185], v[44:47]
	v_mfma_f32_16x16x32_bf16 v[40:43], v[160:163], v[182:185], v[40:43]
	v_mfma_f32_16x16x32_bf16 v[28:31], v[152:155], v[190:193], v[28:31]
	v_mfma_f32_16x16x32_bf16 v[24:27], v[160:163], v[190:193], v[24:27]
	v_mfma_f32_16x16x32_bf16 v[12:15], v[152:155], v[206:209], v[12:15]
	v_mfma_f32_16x16x32_bf16 v[8:11], v[160:163], v[206:209], v[8:11]
	s_setprio 0
	s_barrier
	s_add_u32 s26, s42, 0x40080
	s_addc_u32 s27, s43, 0
	s_add_i32 s42, s44, s17
	v_lshl_add_u64 v[142:143], s[26:27], 0, v[172:173]
	s_mov_b32 m0, s42
	s_nop 0
	global_load_lds_dwordx4 v[142:143], off
	v_lshl_add_u64 v[142:143], s[26:27], 0, v[132:133]
	s_add_i32 m0, s42, 0x2000
	s_nop 0
	global_load_lds_dwordx4 v[142:143], off
	s_waitcnt vmcnt(6)
	s_barrier
	s_setprio 1
	v_mfma_f32_16x16x32_bf16 v[52:55], v[210:213], v[164:167], v[52:55]
	v_mfma_f32_16x16x32_bf16 v[48:51], v[218:221], v[164:167], v[48:51]
	v_mfma_f32_16x16x32_bf16 v[36:39], v[210:213], v[178:181], v[36:39]
	v_mfma_f32_16x16x32_bf16 v[32:35], v[218:221], v[178:181], v[32:35]
	v_mfma_f32_16x16x32_bf16 v[20:23], v[210:213], v[186:189], v[20:23]
	v_mfma_f32_16x16x32_bf16 v[16:19], v[218:221], v[186:189], v[16:19]
	v_mfma_f32_16x16x32_bf16 v[4:7], v[210:213], v[202:205], v[4:7]
	v_mfma_f32_16x16x32_bf16 v[0:3], v[218:221], v[202:205], v[0:3]
	v_mfma_f32_16x16x32_bf16 v[52:55], v[214:217], v[174:177], v[52:55]
	v_mfma_f32_16x16x32_bf16 v[48:51], v[222:225], v[174:177], v[48:51]
	v_mfma_f32_16x16x32_bf16 v[36:39], v[214:217], v[182:185], v[36:39]
	v_mfma_f32_16x16x32_bf16 v[32:35], v[222:225], v[182:185], v[32:35]
	v_mfma_f32_16x16x32_bf16 v[20:23], v[214:217], v[190:193], v[20:23]
	v_mfma_f32_16x16x32_bf16 v[16:19], v[222:225], v[190:193], v[16:19]
	v_mfma_f32_16x16x32_bf16 v[4:7], v[214:217], v[206:209], v[4:7]
	v_mfma_f32_16x16x32_bf16 v[0:3], v[222:225], v[206:209], v[0:3]
	s_setprio 0
	s_add_i32 s25, s25, 2
	s_add_u32 s0, s0, 0x100
	s_addc_u32 s1, s1, 0
	s_cmp_gt_u32 s25, 13
	s_barrier
	s_cbranch_scc0 .LBB0_199
	v_mov_b32_e32 v138, v144
	v_mov_b32_e32 v140, v145
	s_lshl_b32 s0, s22, 8
	s_add_i32 s0, s0, s59
	v_add_u32_e32 v138, s0, v138
	v_cndmask_b32_e64 v141, 0, 1, s[78:79]
	v_ashrrev_i32_e32 v139, 31, v138
	v_cmp_ne_u32_e64 s[42:43], 1, v141
	s_andn2_b64 vcc, exec, s[78:79]
	v_mov_b32_e32 v150, 1.0
	s_cbranch_vccnz .LBB0_202
	v_lshl_add_u64 v[142:143], v[138:139], 2, s[64:65]
	global_load_dword v139, v[142:143], off
	global_load_dword v225, v[142:143], off offset:64
	global_load_dword v226, v[142:143], off offset:128
	global_load_dword v227, v[142:143], off offset:192
	global_load_dword v228, v[142:143], off offset:512
	global_load_dword v229, v[142:143], off offset:576
	global_load_dword v230, v[142:143], off offset:640
	global_load_dword v231, v[142:143], off offset:704
	s_waitcnt vmcnt(0)
	v_fmamk_f32 v139, v139, 0x3a800000, v197
	v_rsq_f32_e32 v150, v139

.LBB0_206:
	s_nop 1
	v_add_u32_e32 v112, 16, v138
	v_ashrrev_i32_e32 v113, 31, v112
	s_and_b64 vcc, exec, s[42:43]
	v_mov_b32_e32 v117, 1.0
	s_cbranch_vccnz .LBB0_208
	v_fmamk_f32 v113, v225, 0x3a800000, v197
	v_rsq_f32_e32 v117, v113

.LBB0_212:
	s_nop 1
	v_add_u32_e32 v96, 32, v138
	v_readlane_b32 s52, v234, 52
	v_readlane_b32 s78, v234, 57
	v_ashrrev_i32_e32 v97, 31, v96
	s_and_b64 vcc, exec, s[42:43]
	v_mov_b32_e32 v101, 1.0
	v_readlane_b32 s53, v234, 53
	v_readlane_b32 s79, v234, 58
	s_cbranch_vccnz .LBB0_214
	v_fmamk_f32 v97, v226, 0x3a800000, v197
	v_rsq_f32_e32 v101, v97

.LBB0_218:
	s_nop 1
	v_add_u32_e32 v80, 48, v138
	v_ashrrev_i32_e32 v81, 31, v80
	s_and_b64 vcc, exec, s[42:43]
	v_mov_b32_e32 v85, 1.0
	s_cbranch_vccnz .LBB0_220
	v_fmamk_f32 v81, v227, 0x3a800000, v197
	v_rsq_f32_e32 v85, v81

.LBB0_224:
	s_nop 1
	v_add_u32_e32 v64, 0x80, v138
	v_ashrrev_i32_e32 v65, 31, v64
	s_and_b64 vcc, exec, s[42:43]
	v_mov_b32_e32 v69, 1.0
	s_cbranch_vccnz .LBB0_226
	v_fmamk_f32 v65, v228, 0x3a800000, v197
	v_rsq_f32_e32 v69, v65

.LBB0_230:
	s_nop 1
	v_add_u32_e32 v48, 0x90, v138
	v_ashrrev_i32_e32 v49, 31, v48
	s_and_b64 vcc, exec, s[42:43]
	v_mov_b32_e32 v53, 1.0
	s_cbranch_vccnz .LBB0_232
	v_fmamk_f32 v49, v229, 0x3a800000, v197
	v_rsq_f32_e32 v53, v49

.LBB0_236:
	s_nop 1
	v_add_u32_e32 v32, 0xa0, v138
	v_ashrrev_i32_e32 v33, 31, v32
	s_and_b64 vcc, exec, s[42:43]
	v_mov_b32_e32 v37, 1.0
	s_cbranch_vccnz .LBB0_238
	v_fmamk_f32 v33, v230, 0x3a800000, v197
	v_rsq_f32_e32 v37, v33

.LBB0_242:
	s_nop 1
	v_add_u32_e32 v16, 0xb0, v138
	v_ashrrev_i32_e32 v17, 31, v16
	s_and_b64 vcc, exec, s[42:43]
	v_mov_b32_e32 v21, 1.0
	s_cbranch_vccnz .LBB0_244
	v_fmamk_f32 v17, v231, 0x3a800000, v197
	v_rsq_f32_e32 v21, v17

.LBB0_464:
	s_cbranch_execz .LBB0_390
	s_lshl_b32 s0, s70, 8
	s_add_i32 s0, s0, s63
	v_add_u32_e32 v138, s0, v153
	v_readlane_b32 s0, v234, 57
	v_readlane_b32 s1, v234, 58
	v_ashrrev_i32_e32 v139, 31, v138
	s_andn2_b64 vcc, exec, s[0:1]
	v_cndmask_b32_e64 v140, 0, 1, s[0:1]
	v_cmp_ne_u32_e64 s[44:45], 1, v140
	v_mov_b32_e32 v146, 1.0
	s_cbranch_vccnz .LBB0_467
	v_lshl_add_u64 v[140:141], v[138:139], 2, s[64:65]
	global_load_dword v139, v[140:141], off
	global_load_dword v225, v[140:141], off offset:64
	global_load_dword v226, v[140:141], off offset:128
	global_load_dword v227, v[140:141], off offset:192
	global_load_dword v228, v[140:141], off offset:512
	global_load_dword v229, v[140:141], off offset:576
	global_load_dword v230, v[140:141], off offset:640
	global_load_dword v231, v[140:141], off offset:704
	s_waitcnt vmcnt(0)
	v_fmamk_f32 v139, v139, 0x3a800000, v197
	v_rsq_f32_e32 v146, v139

.LBB0_471:
	s_nop 1
	v_add_u32_e32 v112, 16, v138
	v_ashrrev_i32_e32 v113, 31, v112
	s_and_b64 vcc, exec, s[44:45]
	v_mov_b32_e32 v117, 1.0
	s_cbranch_vccnz .LBB0_473
	v_fmamk_f32 v113, v225, 0x3a800000, v197
	v_rsq_f32_e32 v117, v113

.LBB0_477:
	s_nop 1
	v_add_u32_e32 v96, 32, v138
	v_ashrrev_i32_e32 v97, 31, v96
	s_and_b64 vcc, exec, s[44:45]
	v_mov_b32_e32 v101, 1.0
	s_cbranch_vccnz .LBB0_479
	v_fmamk_f32 v97, v226, 0x3a800000, v197
	v_rsq_f32_e32 v101, v97

.LBB0_483:
	s_nop 1
	v_add_u32_e32 v80, 48, v138
	v_ashrrev_i32_e32 v81, 31, v80
	s_and_b64 vcc, exec, s[44:45]
	v_mov_b32_e32 v85, 1.0
	s_cbranch_vccnz .LBB0_485
	v_fmamk_f32 v81, v227, 0x3a800000, v197
	v_rsq_f32_e32 v85, v81

.LBB0_489:
	s_nop 1
	v_add_u32_e32 v64, 0x80, v138
	v_ashrrev_i32_e32 v65, 31, v64
	s_and_b64 vcc, exec, s[44:45]
	v_mov_b32_e32 v69, 1.0
	s_cbranch_vccnz .LBB0_491
	v_fmamk_f32 v65, v228, 0x3a800000, v197
	v_rsq_f32_e32 v69, v65

.LBB0_495:
	s_nop 1
	v_add_u32_e32 v48, 0x90, v138
	v_ashrrev_i32_e32 v49, 31, v48
	s_and_b64 vcc, exec, s[44:45]
	v_mov_b32_e32 v53, 1.0
	s_cbranch_vccnz .LBB0_497
	v_fmamk_f32 v49, v229, 0x3a800000, v197
	v_rsq_f32_e32 v53, v49

.LBB0_501:
	s_nop 1
	v_add_u32_e32 v32, 0xa0, v138
	v_ashrrev_i32_e32 v33, 31, v32
	s_and_b64 vcc, exec, s[44:45]
	v_mov_b32_e32 v37, 1.0
	s_cbranch_vccnz .LBB0_503
	v_fmamk_f32 v33, v230, 0x3a800000, v197
	v_rsq_f32_e32 v37, v33

.LBB0_507:
	s_nop 1
	v_add_u32_e32 v16, 0xb0, v138
	v_ashrrev_i32_e32 v17, 31, v16
	s_and_b64 vcc, exec, s[44:45]
	v_mov_b32_e32 v21, 1.0
	s_cbranch_vccnz .LBB0_509
	v_fmamk_f32 v17, v231, 0x3a800000, v197
	v_rsq_f32_e32 v21, v17

.LBB0_1098:
	s_or_b64 exec, exec, s[4:5]
	s_barrier
	global_load_dword v204, v[134:135], off sc1
	global_load_dword v205, v[144:145], off sc1
	global_load_dword v206, v[148:149], off sc1
	global_load_dword v207, v[152:153], off sc1
	global_load_dword v208, v[156:157], off sc1
	global_load_dword v209, v[160:161], off sc1
	global_load_dword v210, v[162:163], off sc1
	global_load_dword v211, v[136:137], off sc1
	v_lshlrev_b64 v[134:135], 2, v[128:129]
	v_lshl_add_u64 v[128:129], s[82:83], 0, v[134:135]
	global_load_dwordx4 v[212:215], v[128:129], off
	global_load_dwordx4 v[216:219], v[128:129], off offset:16
	global_load_dwordx4 v[220:223], v[128:129], off offset:512
	global_load_dwordx4 v[224:227], v[128:129], off offset:528
	s_waitcnt vmcnt(0)
	v_mov_b32_e32 v138, v204
	s_nop 1
	v_mov_b64_e32 v[164:165], v[212:213]
	v_mov_b64_e32 v[166:167], v[214:215]
	v_mov_b64_e32 v[174:175], v[216:217]
	v_mov_b64_e32 v[176:177], v[218:219]
	v_lshl_add_u64 v[130:131], v[130:131], 0, v[134:135]
	s_mov_b64 s[4:5], 0
	v_fmamk_f32 v138, v138, 0x3a800000, v197
	v_rsq_f32_e32 v138, v138
	s_nop 0
	v_pk_mul_f32 v[124:125], v[124:125], v[138:139] op_sel_hi:[1,0]
	v_pk_mul_f32 v[126:127], v[126:127], v[138:139] op_sel_hi:[1,0]
	v_pk_mul_f32 v[178:179], v[120:121], v[138:139] op_sel_hi:[1,0]
	v_pk_mul_f32 v[180:181], v[122:123], v[138:139] op_sel_hi:[1,0]
	v_pk_mul_f32 v[122:123], v[166:167], v[126:127]
	v_pk_mul_f32 v[120:121], v[164:165], v[124:125]
	v_pk_mul_f32 v[126:127], v[176:177], v[180:181]
	v_pk_mul_f32 v[124:125], v[174:175], v[178:179]
	global_store_dwordx4 v[130:131], v[120:123], off
	global_store_dwordx4 v[130:131], v[124:127], off offset:16
	s_nop 1
	v_mov_b64_e32 v[120:121], v[220:221]
	v_mov_b64_e32 v[122:123], v[222:223]
	v_mov_b64_e32 v[124:125], v[224:225]
	v_mov_b64_e32 v[126:127], v[226:227]
	v_pk_mul_f32 v[112:113], v[112:113], v[138:139] op_sel_hi:[1,0]
	v_pk_mul_f32 v[114:115], v[114:115], v[138:139] op_sel_hi:[1,0]
	v_pk_mul_f32 v[164:165], v[104:105], v[138:139] op_sel_hi:[1,0]
	v_pk_mul_f32 v[138:139], v[106:107], v[138:139] op_sel_hi:[1,0]
	v_pk_mul_f32 v[106:107], v[122:123], v[114:115]
	v_pk_mul_f32 v[104:105], v[120:121], v[112:113]
	v_pk_mul_f32 v[114:115], v[126:127], v[138:139]
	v_pk_mul_f32 v[112:113], v[124:125], v[164:165]
	global_store_dwordx4 v[130:131], v[104:107], off offset:512
	global_store_dwordx4 v[130:131], v[112:115], off offset:528
	v_mov_b32_e32 v120, v205
	s_nop 0
	s_nop 1
	v_mov_b64_e32 v[104:105], v[212:213]
	v_mov_b64_e32 v[106:107], v[214:215]
	v_mov_b64_e32 v[112:113], v[216:217]
	v_mov_b64_e32 v[114:115], v[218:219]
	v_lshl_add_u64 v[122:123], v[132:133], 0, v[134:135]
	v_fmamk_f32 v120, v120, 0x3a800000, v197
	v_rsq_f32_e32 v120, v120
	s_nop 0
	v_pk_mul_f32 v[116:117], v[116:117], v[120:121] op_sel_hi:[1,0]
	v_pk_mul_f32 v[118:119], v[118:119], v[120:121] op_sel_hi:[1,0]
	v_pk_mul_f32 v[108:109], v[108:109], v[120:121] op_sel_hi:[1,0]
	v_pk_mul_f32 v[110:111], v[110:111], v[120:121] op_sel_hi:[1,0]
	v_pk_mul_f32 v[106:107], v[106:107], v[118:119]
	v_pk_mul_f32 v[104:105], v[104:105], v[116:117]
	v_pk_mul_f32 v[110:111], v[114:115], v[110:111]
	v_pk_mul_f32 v[108:109], v[112:113], v[108:109]
	global_store_dwordx4 v[122:123], v[104:107], off
	global_store_dwordx4 v[122:123], v[108:111], off offset:16
	s_nop 1
	v_mov_b64_e32 v[104:105], v[220:221]
	v_mov_b64_e32 v[106:107], v[222:223]
	v_mov_b64_e32 v[108:109], v[224:225]
	v_mov_b64_e32 v[110:111], v[226:227]
	v_pk_mul_f32 v[96:97], v[96:97], v[120:121] op_sel_hi:[1,0]
	v_pk_mul_f32 v[98:99], v[98:99], v[120:121] op_sel_hi:[1,0]
	v_pk_mul_f32 v[112:113], v[88:89], v[120:121] op_sel_hi:[1,0]
	v_pk_mul_f32 v[114:115], v[90:91], v[120:121] op_sel_hi:[1,0]
	v_pk_mul_f32 v[90:91], v[106:107], v[98:99]
	v_pk_mul_f32 v[88:89], v[104:105], v[96:97]
	v_pk_mul_f32 v[98:99], v[110:111], v[114:115]
	v_pk_mul_f32 v[96:97], v[108:109], v[112:113]
	global_store_dwordx4 v[122:123], v[88:91], off offset:512
	global_store_dwordx4 v[122:123], v[96:99], off offset:528
	v_mov_b32_e32 v104, v206
	s_nop 0
	s_nop 1
	v_mov_b64_e32 v[88:89], v[212:213]
	v_mov_b64_e32 v[90:91], v[214:215]
	v_mov_b64_e32 v[96:97], v[216:217]
	v_mov_b64_e32 v[98:99], v[218:219]
	v_lshl_add_u64 v[106:107], v[142:143], 0, v[134:135]
	v_fmamk_f32 v104, v104, 0x3a800000, v197
	v_rsq_f32_e32 v104, v104
	s_nop 0
	v_pk_mul_f32 v[100:101], v[100:101], v[104:105] op_sel_hi:[1,0]
	v_pk_mul_f32 v[102:103], v[102:103], v[104:105] op_sel_hi:[1,0]
	v_pk_mul_f32 v[92:93], v[92:93], v[104:105] op_sel_hi:[1,0]
	v_pk_mul_f32 v[94:95], v[94:95], v[104:105] op_sel_hi:[1,0]
	v_pk_mul_f32 v[90:91], v[90:91], v[102:103]
	v_pk_mul_f32 v[88:89], v[88:89], v[100:101]
	v_pk_mul_f32 v[94:95], v[98:99], v[94:95]
	v_pk_mul_f32 v[92:93], v[96:97], v[92:93]
	global_store_dwordx4 v[106:107], v[88:91], off
	global_store_dwordx4 v[106:107], v[92:95], off offset:16
	s_nop 1
	v_mov_b64_e32 v[88:89], v[220:221]
	v_mov_b64_e32 v[90:91], v[222:223]
	v_mov_b64_e32 v[92:93], v[224:225]
	v_mov_b64_e32 v[94:95], v[226:227]
	v_pk_mul_f32 v[80:81], v[80:81], v[104:105] op_sel_hi:[1,0]
	v_pk_mul_f32 v[82:83], v[82:83], v[104:105] op_sel_hi:[1,0]
	v_pk_mul_f32 v[96:97], v[72:73], v[104:105] op_sel_hi:[1,0]
	v_pk_mul_f32 v[98:99], v[74:75], v[104:105] op_sel_hi:[1,0]
	v_pk_mul_f32 v[74:75], v[90:91], v[82:83]
	v_pk_mul_f32 v[72:73], v[88:89], v[80:81]
	v_pk_mul_f32 v[82:83], v[94:95], v[98:99]
	v_pk_mul_f32 v[80:81], v[92:93], v[96:97]
	global_store_dwordx4 v[106:107], v[72:75], off offset:512
	global_store_dwordx4 v[106:107], v[80:83], off offset:528
	v_mov_b32_e32 v88, v207
	s_nop 0
	s_nop 1
	v_mov_b64_e32 v[72:73], v[212:213]
	v_mov_b64_e32 v[74:75], v[214:215]
	v_mov_b64_e32 v[80:81], v[216:217]
	v_mov_b64_e32 v[82:83], v[218:219]
	v_lshl_add_u64 v[90:91], v[146:147], 0, v[134:135]
	v_fmamk_f32 v88, v88, 0x3a800000, v197
	v_rsq_f32_e32 v88, v88
	s_nop 0
	v_pk_mul_f32 v[84:85], v[84:85], v[88:89] op_sel_hi:[1,0]
	v_pk_mul_f32 v[86:87], v[86:87], v[88:89] op_sel_hi:[1,0]
	v_pk_mul_f32 v[76:77], v[76:77], v[88:89] op_sel_hi:[1,0]
	v_pk_mul_f32 v[78:79], v[78:79], v[88:89] op_sel_hi:[1,0]
	v_pk_mul_f32 v[74:75], v[74:75], v[86:87]
	v_pk_mul_f32 v[72:73], v[72:73], v[84:85]
	v_pk_mul_f32 v[78:79], v[82:83], v[78:79]
	v_pk_mul_f32 v[76:77], v[80:81], v[76:77]
	global_store_dwordx4 v[90:91], v[72:75], off
	global_store_dwordx4 v[90:91], v[76:79], off offset:16
	s_nop 1
	v_mov_b64_e32 v[72:73], v[220:221]
	v_mov_b64_e32 v[74:75], v[222:223]
	v_mov_b64_e32 v[76:77], v[224:225]
	v_mov_b64_e32 v[78:79], v[226:227]
	v_pk_mul_f32 v[68:69], v[68:69], v[88:89] op_sel_hi:[1,0]
	v_pk_mul_f32 v[70:71], v[70:71], v[88:89] op_sel_hi:[1,0]
	v_pk_mul_f32 v[80:81], v[64:65], v[88:89] op_sel_hi:[1,0]
	v_pk_mul_f32 v[82:83], v[66:67], v[88:89] op_sel_hi:[1,0]
	v_pk_mul_f32 v[66:67], v[74:75], v[70:71]
	v_pk_mul_f32 v[64:65], v[72:73], v[68:69]
	v_pk_mul_f32 v[70:71], v[78:79], v[82:83]
	v_pk_mul_f32 v[68:69], v[76:77], v[80:81]
	global_store_dwordx4 v[90:91], v[64:67], off offset:512
	global_store_dwordx4 v[90:91], v[68:71], off offset:528
	v_mov_b32_e32 v72, v208
	s_nop 0
	s_nop 1
	v_mov_b64_e32 v[64:65], v[212:213]
	v_mov_b64_e32 v[66:67], v[214:215]
	v_mov_b64_e32 v[68:69], v[216:217]
	v_mov_b64_e32 v[70:71], v[218:219]
	v_lshl_add_u64 v[74:75], v[150:151], 0, v[134:135]
	v_fmamk_f32 v72, v72, 0x3a800000, v197
	v_rsq_f32_e32 v72, v72
	s_nop 0
	v_pk_mul_f32 v[60:61], v[60:61], v[72:73] op_sel_hi:[1,0]
	v_pk_mul_f32 v[62:63], v[62:63], v[72:73] op_sel_hi:[1,0]
	v_pk_mul_f32 v[76:77], v[56:57], v[72:73] op_sel_hi:[1,0]
	v_pk_mul_f32 v[78:79], v[58:59], v[72:73] op_sel_hi:[1,0]
	v_pk_mul_f32 v[58:59], v[66:67], v[62:63]
	v_pk_mul_f32 v[56:57], v[64:65], v[60:61]
	v_pk_mul_f32 v[62:63], v[70:71], v[78:79]
	v_pk_mul_f32 v[60:61], v[68:69], v[76:77]
	global_store_dwordx4 v[74:75], v[56:59], off
	global_store_dwordx4 v[74:75], v[60:63], off offset:16
	s_nop 1
	v_mov_b64_e32 v[56:57], v[220:221]
	v_mov_b64_e32 v[58:59], v[222:223]
	v_mov_b64_e32 v[60:61], v[224:225]
	v_mov_b64_e32 v[62:63], v[226:227]
	v_pk_mul_f32 v[48:49], v[48:49], v[72:73] op_sel_hi:[1,0]
	v_pk_mul_f32 v[50:51], v[50:51], v[72:73] op_sel_hi:[1,0]
	v_pk_mul_f32 v[64:65], v[40:41], v[72:73] op_sel_hi:[1,0]
	v_pk_mul_f32 v[66:67], v[42:43], v[72:73] op_sel_hi:[1,0]
	v_pk_mul_f32 v[42:43], v[58:59], v[50:51]
	v_pk_mul_f32 v[40:41], v[56:57], v[48:49]
	v_pk_mul_f32 v[50:51], v[62:63], v[66:67]
	v_pk_mul_f32 v[48:49], v[60:61], v[64:65]
	global_store_dwordx4 v[74:75], v[40:43], off offset:512
	global_store_dwordx4 v[74:75], v[48:51], off offset:528
	v_mov_b32_e32 v56, v209
	s_nop 0
	s_nop 1
	v_mov_b64_e32 v[40:41], v[212:213]
	v_mov_b64_e32 v[42:43], v[214:215]
	v_mov_b64_e32 v[48:49], v[216:217]
	v_mov_b64_e32 v[50:51], v[218:219]
	v_lshl_add_u64 v[58:59], v[154:155], 0, v[134:135]
	v_fmamk_f32 v56, v56, 0x3a800000, v197
	v_rsq_f32_e32 v56, v56
	s_nop 0
	v_pk_mul_f32 v[52:53], v[52:53], v[56:57] op_sel_hi:[1,0]
	v_pk_mul_f32 v[54:55], v[54:55], v[56:57] op_sel_hi:[1,0]
	v_pk_mul_f32 v[44:45], v[44:45], v[56:57] op_sel_hi:[1,0]
	v_pk_mul_f32 v[46:47], v[46:47], v[56:57] op_sel_hi:[1,0]
	v_pk_mul_f32 v[42:43], v[42:43], v[54:55]
	v_pk_mul_f32 v[40:41], v[40:41], v[52:53]
	v_pk_mul_f32 v[46:47], v[50:51], v[46:47]
	v_pk_mul_f32 v[44:45], v[48:49], v[44:45]
	global_store_dwordx4 v[58:59], v[40:43], off
	global_store_dwordx4 v[58:59], v[44:47], off offset:16
	s_nop 1
	v_mov_b64_e32 v[40:41], v[220:221]
	v_mov_b64_e32 v[42:43], v[222:223]
	v_mov_b64_e32 v[44:45], v[224:225]
	v_mov_b64_e32 v[46:47], v[226:227]
	v_pk_mul_f32 v[32:33], v[32:33], v[56:57] op_sel_hi:[1,0]
	v_pk_mul_f32 v[34:35], v[34:35], v[56:57] op_sel_hi:[1,0]
	v_pk_mul_f32 v[48:49], v[24:25], v[56:57] op_sel_hi:[1,0]
	v_pk_mul_f32 v[50:51], v[26:27], v[56:57] op_sel_hi:[1,0]
	v_pk_mul_f32 v[26:27], v[42:43], v[34:35]
	v_pk_mul_f32 v[24:25], v[40:41], v[32:33]
	v_pk_mul_f32 v[34:35], v[46:47], v[50:51]
	v_pk_mul_f32 v[32:33], v[44:45], v[48:49]
	global_store_dwordx4 v[58:59], v[24:27], off offset:512
	global_store_dwordx4 v[58:59], v[32:35], off offset:528
	v_mov_b32_e32 v40, v210
	s_nop 0
	s_nop 1
	v_mov_b64_e32 v[24:25], v[212:213]
	v_mov_b64_e32 v[26:27], v[214:215]
	v_mov_b64_e32 v[32:33], v[216:217]
	v_mov_b64_e32 v[34:35], v[218:219]
	v_lshl_add_u64 v[42:43], v[158:159], 0, v[134:135]
	v_fmamk_f32 v40, v40, 0x3a800000, v197
	v_rsq_f32_e32 v40, v40
	s_nop 0
	v_pk_mul_f32 v[36:37], v[36:37], v[40:41] op_sel_hi:[1,0]
	v_pk_mul_f32 v[38:39], v[38:39], v[40:41] op_sel_hi:[1,0]
	v_pk_mul_f32 v[28:29], v[28:29], v[40:41] op_sel_hi:[1,0]
	v_pk_mul_f32 v[30:31], v[30:31], v[40:41] op_sel_hi:[1,0]
	v_pk_mul_f32 v[26:27], v[26:27], v[38:39]
	v_pk_mul_f32 v[24:25], v[24:25], v[36:37]
	v_pk_mul_f32 v[30:31], v[34:35], v[30:31]
	v_pk_mul_f32 v[28:29], v[32:33], v[28:29]
	global_store_dwordx4 v[42:43], v[24:27], off
	global_store_dwordx4 v[42:43], v[28:31], off offset:16
	s_nop 1
	v_mov_b64_e32 v[24:25], v[220:221]
	v_mov_b64_e32 v[26:27], v[222:223]
	v_mov_b64_e32 v[28:29], v[224:225]
	v_mov_b64_e32 v[30:31], v[226:227]
	v_pk_mul_f32 v[16:17], v[16:17], v[40:41] op_sel_hi:[1,0]
	v_pk_mul_f32 v[18:19], v[18:19], v[40:41] op_sel_hi:[1,0]
	v_pk_mul_f32 v[32:33], v[8:9], v[40:41] op_sel_hi:[1,0]
	v_pk_mul_f32 v[34:35], v[10:11], v[40:41] op_sel_hi:[1,0]
	v_pk_mul_f32 v[10:11], v[26:27], v[18:19]
	v_pk_mul_f32 v[8:9], v[24:25], v[16:17]
	v_pk_mul_f32 v[18:19], v[30:31], v[34:35]
	v_pk_mul_f32 v[16:17], v[28:29], v[32:33]
	global_store_dwordx4 v[42:43], v[8:11], off offset:512
	global_store_dwordx4 v[42:43], v[16:19], off offset:528
	v_mov_b32_e32 v24, v211
	s_nop 0
	s_nop 1
	v_mov_b64_e32 v[8:9], v[212:213]
	v_mov_b64_e32 v[10:11], v[214:215]
	v_mov_b64_e32 v[16:17], v[216:217]
	v_mov_b64_e32 v[18:19], v[218:219]
	v_lshl_add_u64 v[26:27], v[140:141], 0, v[134:135]
	v_fmamk_f32 v24, v24, 0x3a800000, v197
	v_rsq_f32_e32 v24, v24
	s_nop 0
	v_pk_mul_f32 v[20:21], v[20:21], v[24:25] op_sel_hi:[1,0]
	v_pk_mul_f32 v[22:23], v[22:23], v[24:25] op_sel_hi:[1,0]
	v_pk_mul_f32 v[12:13], v[12:13], v[24:25] op_sel_hi:[1,0]
	v_pk_mul_f32 v[14:15], v[14:15], v[24:25] op_sel_hi:[1,0]
	v_pk_mul_f32 v[10:11], v[10:11], v[22:23]
	v_pk_mul_f32 v[8:9], v[8:9], v[20:21]
	v_pk_mul_f32 v[14:15], v[18:19], v[14:15]
	v_pk_mul_f32 v[12:13], v[16:17], v[12:13]
	global_store_dwordx4 v[26:27], v[8:11], off
	global_store_dwordx4 v[26:27], v[12:15], off offset:16
	s_nop 1
	v_mov_b64_e32 v[8:9], v[220:221]
	v_mov_b64_e32 v[10:11], v[222:223]
	v_mov_b64_e32 v[12:13], v[224:225]
	v_mov_b64_e32 v[14:15], v[226:227]
	v_pk_mul_f32 v[4:5], v[4:5], v[24:25] op_sel_hi:[1,0]
	v_pk_mul_f32 v[6:7], v[6:7], v[24:25] op_sel_hi:[1,0]
	v_pk_mul_f32 v[16:17], v[0:1], v[24:25] op_sel_hi:[1,0]
	v_pk_mul_f32 v[18:19], v[2:3], v[24:25] op_sel_hi:[1,0]
	v_pk_mul_f32 v[2:3], v[10:11], v[6:7]
	v_pk_mul_f32 v[0:1], v[8:9], v[4:5]
	v_pk_mul_f32 v[6:7], v[14:15], v[18:19]
	v_pk_mul_f32 v[4:5], v[12:13], v[16:17]
	global_store_dwordx4 v[26:27], v[0:3], off offset:512
	global_store_dwordx4 v[26:27], v[4:7], off offset:528
	s_cbranch_execz .LBB0_1005
	s_branch .LBB0_1004
